# EpiGate: lane-permuted (quad-coalesced) gate/o loads and stores via ds_bpermute
# baseline (speedup 1.0000x reference)
.LBB0_207:
	s_add_u32 s0, s50, 0x210080
	s_addc_u32 s1, s51, 0
	s_mov_b32 m0, s72
	s_nop 0
	global_load_lds_dwordx4 v0, s[0:1]
	s_cmp_lg_u32 s78, 2
	s_mov_b32 m0, s74
	s_nop 0
	global_load_lds_dwordx4 v149, s[0:1]
	v_bfe_u32 v130, v195, 4, 2
	v_bfe_u32 v131, v195, 2, 2
	v_and_b32_e32 v132, 3, v195
	v_and_b32_e32 v133, 0xfffffff0, v151
	v_lshl_add_u32 v133, v130, 2, v133
	v_add_u32_e32 v133, v133, v131
	v_and_b32_e32 v134, 0xffffffe7, v152
	v_lshl_add_u32 v134, v132, 3, v134
	v_lshlrev_b32_e32 v155, 4, v131
	v_lshl_add_u32 v155, v132, 2, v155
	v_add_lshl_u32 v155, v155, v130, 2
	v_lshlrev_b32_e32 v156, 4, v132
	v_lshl_add_u32 v156, v130, 2, v156
	v_add_lshl_u32 v156, v156, v131, 2
	v_lshl_or_b32 v246, s4, 8, v134
	v_lshl_add_u32 v248, s79, 8, v133
	v_ashrrev_i32_e32 v247, 31, v246
	v_ashrrev_i32_e32 v249, 31, v248
	s_cmp_lg_u32 s78, 2
	s_cselect_b64 s[0:1], -1, 0
	s_cmp_lg_u32 s4, 3
	s_cselect_b64 s[4:5], -1, 0
	s_or_b64 s[0:1], s[0:1], s[4:5]
	s_and_b64 vcc, exec, s[0:1]
	s_cbranch_vccz .Leg_gl2
	v_mov_b64_e32 v[144:145], s[28:29]
	v_mad_i64_i32 v[144:145], s[4:5], v248, s83, v[144:145]
	s_lshl_b32 s4, s78, 10
	s_ashr_i32 s5, s4, 31
	v_lshl_add_u64 v[144:145], s[4:5], 1, v[144:145]
	v_lshl_add_u64 v[138:139], v[246:247], 1, v[144:145]
	s_mov_b64 s[0:1], 0x42000
	s_mov_b64 s[4:5], 0x14a000
	s_branch .Leg_cont

.Leg_cont:
	v_lshlrev_b64 v[144:145], 11, v[248:249]
	v_lshl_add_u64 v[144:145], s[22:23], 0, v[144:145]
	v_lshl_add_u64 v[140:141], v[246:247], 1, v[144:145]
	v_mov_b64_e32 v[142:143], v[140:141]
	s_mov_b64 s[34:35], 0x8000
	s_mov_b64 s[38:39], 0x28000
	s_cmp_gt_i32 s78, 0
	s_cselect_b64 s[6:7], -1, 0
	global_load_dwordx4 v[210:213], v[138:139], off
	global_load_dwordx4 v[214:217], v[140:141], off
	global_load_dwordx4 v[218:221], v[138:139], off offset:256
	global_load_dwordx4 v[222:225], v[140:141], off offset:256
	v_lshl_add_u64 v[138:139], v[138:139], 0, s[0:1]
	v_lshl_add_u64 v[140:141], v[140:141], 0, s[34:35]
	global_load_dwordx4 v[226:229], v[138:139], off
	global_load_dwordx4 v[230:233], v[140:141], off
	global_load_dwordx4 v[234:237], v[138:139], off offset:256
	global_load_dwordx4 v[238:241], v[140:141], off offset:256
	v_lshl_add_u64 v[138:139], v[138:139], 0, s[0:1]
	v_lshl_add_u64 v[140:141], v[140:141], 0, s[34:35]
	global_load_dwordx4 v[182:185], v[138:139], off
	global_load_dwordx4 v[186:189], v[140:141], off
	global_load_dwordx4 v[190:193], v[138:139], off offset:256
	global_load_dwordx4 v[242:245], v[140:141], off offset:256
	v_lshl_add_u64 v[138:139], v[138:139], 0, s[0:1]
	v_lshl_add_u64 v[140:141], v[140:141], 0, s[34:35]
	s_waitcnt vmcnt(8)
	ds_bpermute_b32 v210, v155, v210
	ds_bpermute_b32 v211, v155, v211
	ds_bpermute_b32 v212, v155, v212
	ds_bpermute_b32 v213, v155, v213
	ds_bpermute_b32 v214, v155, v214
	ds_bpermute_b32 v215, v155, v215
	ds_bpermute_b32 v216, v155, v216
	ds_bpermute_b32 v217, v155, v217
	ds_bpermute_b32 v218, v155, v218
	ds_bpermute_b32 v219, v155, v219
	ds_bpermute_b32 v220, v155, v220
	ds_bpermute_b32 v221, v155, v221
	ds_bpermute_b32 v222, v155, v222
	ds_bpermute_b32 v223, v155, v223
	ds_bpermute_b32 v224, v155, v224
	ds_bpermute_b32 v225, v155, v225
	s_waitcnt lgkmcnt(0)
	v_cndmask_b32_e64 v214, 0, v214, s[6:7]
	v_cndmask_b32_e64 v215, 0, v215, s[6:7]
	v_cndmask_b32_e64 v216, 0, v216, s[6:7]
	v_cndmask_b32_e64 v217, 0, v217, s[6:7]
	v_lshlrev_b32_e32 v130, 16, v210
	v_and_b32_e32 v131, 0xffff0000, v210
	v_lshlrev_b32_e32 v132, 16, v211
	v_and_b32_e32 v133, 0xffff0000, v211
	v_mul_f32_e32 v130, 0xbfb8aa3b, v130
	v_mul_f32_e32 v131, 0xbfb8aa3b, v131
	v_mul_f32_e32 v132, 0xbfb8aa3b, v132
	v_mul_f32_e32 v133, 0xbfb8aa3b, v133
	v_exp_f32_e32 v130, v130
	v_exp_f32_e32 v131, v131
	v_exp_f32_e32 v132, v132
	v_exp_f32_e32 v133, v133
	v_lshlrev_b32_e32 v134, 16, v214
	v_and_b32_e32 v135, 0xffff0000, v214
	v_lshlrev_b32_e32 v136, 16, v215
	v_and_b32_e32 v137, 0xffff0000, v215
	v_add_f32_e32 v130, 1.0, v130
	v_add_f32_e32 v131, 1.0, v131
	v_add_f32_e32 v132, 1.0, v132
	v_add_f32_e32 v133, 1.0, v133
	v_rcp_f32_e32 v130, v130
	v_rcp_f32_e32 v131, v131
	v_rcp_f32_e32 v132, v132
	v_rcp_f32_e32 v133, v133
	s_nop 0
	v_fmac_f32_e32 v134, v126, v130
	v_fmac_f32_e32 v135, v127, v131
	v_fmac_f32_e32 v136, v128, v132
	v_fmac_f32_e32 v137, v129, v133
	v_cvt_pk_bf16_f32 v126, v134, v135
	v_cvt_pk_bf16_f32 v127, v136, v137
	v_lshlrev_b32_e32 v130, 16, v212
	v_and_b32_e32 v131, 0xffff0000, v212
	v_lshlrev_b32_e32 v132, 16, v213
	v_and_b32_e32 v133, 0xffff0000, v213
	v_mul_f32_e32 v130, 0xbfb8aa3b, v130
	v_mul_f32_e32 v131, 0xbfb8aa3b, v131
	v_mul_f32_e32 v132, 0xbfb8aa3b, v132
	v_mul_f32_e32 v133, 0xbfb8aa3b, v133
	v_exp_f32_e32 v130, v130
	v_exp_f32_e32 v131, v131
	v_exp_f32_e32 v132, v132
	v_exp_f32_e32 v133, v133
	v_lshlrev_b32_e32 v134, 16, v216
	v_and_b32_e32 v135, 0xffff0000, v216
	v_lshlrev_b32_e32 v136, 16, v217
	v_and_b32_e32 v137, 0xffff0000, v217
	v_add_f32_e32 v130, 1.0, v130
	v_add_f32_e32 v131, 1.0, v131
	v_add_f32_e32 v132, 1.0, v132
	v_add_f32_e32 v133, 1.0, v133
	v_rcp_f32_e32 v130, v130
	v_rcp_f32_e32 v131, v131
	v_rcp_f32_e32 v132, v132
	v_rcp_f32_e32 v133, v133
	s_nop 0
	v_fmac_f32_e32 v134, v122, v130
	v_fmac_f32_e32 v135, v123, v131
	v_fmac_f32_e32 v136, v124, v132
	v_fmac_f32_e32 v137, v125, v133
	v_cvt_pk_bf16_f32 v128, v134, v135
	v_cvt_pk_bf16_f32 v129, v136, v137
	v_cndmask_b32_e64 v222, 0, v222, s[6:7]
	v_cndmask_b32_e64 v223, 0, v223, s[6:7]
	v_cndmask_b32_e64 v224, 0, v224, s[6:7]
	v_cndmask_b32_e64 v225, 0, v225, s[6:7]
	v_lshlrev_b32_e32 v130, 16, v218
	v_and_b32_e32 v131, 0xffff0000, v218
	v_lshlrev_b32_e32 v132, 16, v219
	v_and_b32_e32 v133, 0xffff0000, v219
	v_mul_f32_e32 v130, 0xbfb8aa3b, v130
	v_mul_f32_e32 v131, 0xbfb8aa3b, v131
	v_mul_f32_e32 v132, 0xbfb8aa3b, v132
	v_mul_f32_e32 v133, 0xbfb8aa3b, v133
	v_exp_f32_e32 v130, v130
	v_exp_f32_e32 v131, v131
	v_exp_f32_e32 v132, v132
	v_exp_f32_e32 v133, v133
	v_lshlrev_b32_e32 v134, 16, v222
	v_and_b32_e32 v135, 0xffff0000, v222
	v_lshlrev_b32_e32 v136, 16, v223
	v_and_b32_e32 v137, 0xffff0000, v223
	v_add_f32_e32 v130, 1.0, v130
	v_add_f32_e32 v131, 1.0, v131
	v_add_f32_e32 v132, 1.0, v132
	v_add_f32_e32 v133, 1.0, v133
	v_rcp_f32_e32 v130, v130
	v_rcp_f32_e32 v131, v131
	v_rcp_f32_e32 v132, v132
	v_rcp_f32_e32 v133, v133
	s_nop 0
	v_fmac_f32_e32 v134, v118, v130
	v_fmac_f32_e32 v135, v119, v131
	v_fmac_f32_e32 v136, v120, v132
	v_fmac_f32_e32 v137, v121, v133
	v_cvt_pk_bf16_f32 v118, v134, v135
	v_cvt_pk_bf16_f32 v119, v136, v137
	v_lshlrev_b32_e32 v130, 16, v220
	v_and_b32_e32 v131, 0xffff0000, v220
	v_lshlrev_b32_e32 v132, 16, v221
	v_and_b32_e32 v133, 0xffff0000, v221
	v_mul_f32_e32 v130, 0xbfb8aa3b, v130
	v_mul_f32_e32 v131, 0xbfb8aa3b, v131
	v_mul_f32_e32 v132, 0xbfb8aa3b, v132
	v_mul_f32_e32 v133, 0xbfb8aa3b, v133
	v_exp_f32_e32 v130, v130
	v_exp_f32_e32 v131, v131
	v_exp_f32_e32 v132, v132
	v_exp_f32_e32 v133, v133
	v_lshlrev_b32_e32 v134, 16, v224
	v_and_b32_e32 v135, 0xffff0000, v224
	v_lshlrev_b32_e32 v136, 16, v225
	v_and_b32_e32 v137, 0xffff0000, v225
	v_add_f32_e32 v130, 1.0, v130
	v_add_f32_e32 v131, 1.0, v131
	v_add_f32_e32 v132, 1.0, v132
	v_add_f32_e32 v133, 1.0, v133
	v_rcp_f32_e32 v130, v130
	v_rcp_f32_e32 v131, v131
	v_rcp_f32_e32 v132, v132
	v_rcp_f32_e32 v133, v133
	s_nop 0
	v_fmac_f32_e32 v134, v114, v130
	v_fmac_f32_e32 v135, v115, v131
	v_fmac_f32_e32 v136, v116, v132
	v_fmac_f32_e32 v137, v117, v133
	v_cvt_pk_bf16_f32 v120, v134, v135
	v_cvt_pk_bf16_f32 v121, v136, v137
	ds_bpermute_b32 v126, v156, v126
	ds_bpermute_b32 v127, v156, v127
	ds_bpermute_b32 v128, v156, v128
	ds_bpermute_b32 v129, v156, v129
	ds_bpermute_b32 v118, v156, v118
	ds_bpermute_b32 v119, v156, v119
	ds_bpermute_b32 v120, v156, v120
	ds_bpermute_b32 v121, v156, v121
	global_load_dwordx4 v[210:213], v[138:139], off
	global_load_dwordx4 v[214:217], v[140:141], off
	global_load_dwordx4 v[218:221], v[138:139], off offset:256
	global_load_dwordx4 v[222:225], v[140:141], off offset:256
	v_lshl_add_u64 v[138:139], v[138:139], 0, s[4:5]
	v_lshl_add_u64 v[140:141], v[140:141], 0, s[38:39]
	s_waitcnt lgkmcnt(0)
	global_store_dwordx4 v[142:143], v[126:129], off
	global_store_dwordx4 v[142:143], v[118:121], off offset:256
	v_lshl_add_u64 v[142:143], v[142:143], 0, s[34:35]
	s_waitcnt vmcnt(10)
	ds_bpermute_b32 v226, v155, v226
	ds_bpermute_b32 v227, v155, v227
	ds_bpermute_b32 v228, v155, v228
	ds_bpermute_b32 v229, v155, v229
	ds_bpermute_b32 v230, v155, v230
	ds_bpermute_b32 v231, v155, v231
	ds_bpermute_b32 v232, v155, v232
	ds_bpermute_b32 v233, v155, v233
	ds_bpermute_b32 v234, v155, v234
	ds_bpermute_b32 v235, v155, v235
	ds_bpermute_b32 v236, v155, v236
	ds_bpermute_b32 v237, v155, v237
	ds_bpermute_b32 v238, v155, v238
	ds_bpermute_b32 v239, v155, v239
	ds_bpermute_b32 v240, v155, v240
	ds_bpermute_b32 v241, v155, v241
	s_waitcnt lgkmcnt(0)
	v_cndmask_b32_e64 v230, 0, v230, s[6:7]
	v_cndmask_b32_e64 v231, 0, v231, s[6:7]
	v_cndmask_b32_e64 v232, 0, v232, s[6:7]
	v_cndmask_b32_e64 v233, 0, v233, s[6:7]
	v_lshlrev_b32_e32 v130, 16, v226
	v_and_b32_e32 v131, 0xffff0000, v226
	v_lshlrev_b32_e32 v132, 16, v227
	v_and_b32_e32 v133, 0xffff0000, v227
	v_mul_f32_e32 v130, 0xbfb8aa3b, v130
	v_mul_f32_e32 v131, 0xbfb8aa3b, v131
	v_mul_f32_e32 v132, 0xbfb8aa3b, v132
	v_mul_f32_e32 v133, 0xbfb8aa3b, v133
	v_exp_f32_e32 v130, v130
	v_exp_f32_e32 v131, v131
	v_exp_f32_e32 v132, v132
	v_exp_f32_e32 v133, v133
	v_lshlrev_b32_e32 v134, 16, v230
	v_and_b32_e32 v135, 0xffff0000, v230
	v_lshlrev_b32_e32 v136, 16, v231
	v_and_b32_e32 v137, 0xffff0000, v231
	v_add_f32_e32 v130, 1.0, v130
	v_add_f32_e32 v131, 1.0, v131
	v_add_f32_e32 v132, 1.0, v132
	v_add_f32_e32 v133, 1.0, v133
	v_rcp_f32_e32 v130, v130
	v_rcp_f32_e32 v131, v131
	v_rcp_f32_e32 v132, v132
	v_rcp_f32_e32 v133, v133
	s_nop 0
	v_fmac_f32_e32 v134, v110, v130
	v_fmac_f32_e32 v135, v111, v131
	v_fmac_f32_e32 v136, v112, v132
	v_fmac_f32_e32 v137, v113, v133
	v_cvt_pk_bf16_f32 v110, v134, v135
	v_cvt_pk_bf16_f32 v111, v136, v137
	v_lshlrev_b32_e32 v130, 16, v228
	v_and_b32_e32 v131, 0xffff0000, v228
	v_lshlrev_b32_e32 v132, 16, v229
	v_and_b32_e32 v133, 0xffff0000, v229
	v_mul_f32_e32 v130, 0xbfb8aa3b, v130
	v_mul_f32_e32 v131, 0xbfb8aa3b, v131
	v_mul_f32_e32 v132, 0xbfb8aa3b, v132
	v_mul_f32_e32 v133, 0xbfb8aa3b, v133
	v_exp_f32_e32 v130, v130
	v_exp_f32_e32 v131, v131
	v_exp_f32_e32 v132, v132
	v_exp_f32_e32 v133, v133
	v_lshlrev_b32_e32 v134, 16, v232
	v_and_b32_e32 v135, 0xffff0000, v232
	v_lshlrev_b32_e32 v136, 16, v233
	v_and_b32_e32 v137, 0xffff0000, v233
	v_add_f32_e32 v130, 1.0, v130
	v_add_f32_e32 v131, 1.0, v131
	v_add_f32_e32 v132, 1.0, v132
	v_add_f32_e32 v133, 1.0, v133
	v_rcp_f32_e32 v130, v130
	v_rcp_f32_e32 v131, v131
	v_rcp_f32_e32 v132, v132
	v_rcp_f32_e32 v133, v133
	s_nop 0
	v_fmac_f32_e32 v134, v106, v130
	v_fmac_f32_e32 v135, v107, v131
	v_fmac_f32_e32 v136, v108, v132
	v_fmac_f32_e32 v137, v109, v133
	v_cvt_pk_bf16_f32 v112, v134, v135
	v_cvt_pk_bf16_f32 v113, v136, v137
	v_cndmask_b32_e64 v238, 0, v238, s[6:7]
	v_cndmask_b32_e64 v239, 0, v239, s[6:7]
	v_cndmask_b32_e64 v240, 0, v240, s[6:7]
	v_cndmask_b32_e64 v241, 0, v241, s[6:7]
	v_lshlrev_b32_e32 v130, 16, v234
	v_and_b32_e32 v131, 0xffff0000, v234
	v_lshlrev_b32_e32 v132, 16, v235
	v_and_b32_e32 v133, 0xffff0000, v235
	v_mul_f32_e32 v130, 0xbfb8aa3b, v130
	v_mul_f32_e32 v131, 0xbfb8aa3b, v131
	v_mul_f32_e32 v132, 0xbfb8aa3b, v132
	v_mul_f32_e32 v133, 0xbfb8aa3b, v133
	v_exp_f32_e32 v130, v130
	v_exp_f32_e32 v131, v131
	v_exp_f32_e32 v132, v132
	v_exp_f32_e32 v133, v133
	v_lshlrev_b32_e32 v134, 16, v238
	v_and_b32_e32 v135, 0xffff0000, v238
	v_lshlrev_b32_e32 v136, 16, v239
	v_and_b32_e32 v137, 0xffff0000, v239
	v_add_f32_e32 v130, 1.0, v130
	v_add_f32_e32 v131, 1.0, v131
	v_add_f32_e32 v132, 1.0, v132
	v_add_f32_e32 v133, 1.0, v133
	v_rcp_f32_e32 v130, v130
	v_rcp_f32_e32 v131, v131
	v_rcp_f32_e32 v132, v132
	v_rcp_f32_e32 v133, v133
	s_nop 0
	v_fmac_f32_e32 v134, v102, v130
	v_fmac_f32_e32 v135, v103, v131
	v_fmac_f32_e32 v136, v104, v132
	v_fmac_f32_e32 v137, v105, v133
	v_cvt_pk_bf16_f32 v102, v134, v135
	v_cvt_pk_bf16_f32 v103, v136, v137
	v_lshlrev_b32_e32 v130, 16, v236
	v_and_b32_e32 v131, 0xffff0000, v236
	v_lshlrev_b32_e32 v132, 16, v237
	v_and_b32_e32 v133, 0xffff0000, v237
	v_mul_f32_e32 v130, 0xbfb8aa3b, v130
	v_mul_f32_e32 v131, 0xbfb8aa3b, v131
	v_mul_f32_e32 v132, 0xbfb8aa3b, v132
	v_mul_f32_e32 v133, 0xbfb8aa3b, v133
	v_exp_f32_e32 v130, v130
	v_exp_f32_e32 v131, v131
	v_exp_f32_e32 v132, v132
	v_exp_f32_e32 v133, v133
	v_lshlrev_b32_e32 v134, 16, v240
	v_and_b32_e32 v135, 0xffff0000, v240
	v_lshlrev_b32_e32 v136, 16, v241
	v_and_b32_e32 v137, 0xffff0000, v241
	v_add_f32_e32 v130, 1.0, v130
	v_add_f32_e32 v131, 1.0, v131
	v_add_f32_e32 v132, 1.0, v132
	v_add_f32_e32 v133, 1.0, v133
	v_rcp_f32_e32 v130, v130
	v_rcp_f32_e32 v131, v131
	v_rcp_f32_e32 v132, v132
	v_rcp_f32_e32 v133, v133
	s_nop 0
	v_fmac_f32_e32 v134, v98, v130
	v_fmac_f32_e32 v135, v99, v131
	v_fmac_f32_e32 v136, v100, v132
	v_fmac_f32_e32 v137, v101, v133
	v_cvt_pk_bf16_f32 v104, v134, v135
	v_cvt_pk_bf16_f32 v105, v136, v137
	ds_bpermute_b32 v110, v156, v110
	ds_bpermute_b32 v111, v156, v111
	ds_bpermute_b32 v112, v156, v112
	ds_bpermute_b32 v113, v156, v113
	ds_bpermute_b32 v102, v156, v102
	ds_bpermute_b32 v103, v156, v103
	ds_bpermute_b32 v104, v156, v104
	ds_bpermute_b32 v105, v156, v105
	global_load_dwordx4 v[226:229], v[138:139], off
	global_load_dwordx4 v[230:233], v[140:141], off
	global_load_dwordx4 v[234:237], v[138:139], off offset:256
	global_load_dwordx4 v[238:241], v[140:141], off offset:256
	v_lshl_add_u64 v[138:139], v[138:139], 0, s[0:1]
	v_lshl_add_u64 v[140:141], v[140:141], 0, s[34:35]
	s_waitcnt lgkmcnt(0)
	global_store_dwordx4 v[142:143], v[110:113], off
	global_store_dwordx4 v[142:143], v[102:105], off offset:256
	v_lshl_add_u64 v[142:143], v[142:143], 0, s[34:35]
	s_waitcnt vmcnt(12)
	ds_bpermute_b32 v182, v155, v182
	ds_bpermute_b32 v183, v155, v183
	ds_bpermute_b32 v184, v155, v184
	ds_bpermute_b32 v185, v155, v185
	ds_bpermute_b32 v186, v155, v186
	ds_bpermute_b32 v187, v155, v187
	ds_bpermute_b32 v188, v155, v188
	ds_bpermute_b32 v189, v155, v189
	ds_bpermute_b32 v190, v155, v190
	ds_bpermute_b32 v191, v155, v191
	ds_bpermute_b32 v192, v155, v192
	ds_bpermute_b32 v193, v155, v193
	ds_bpermute_b32 v242, v155, v242
	ds_bpermute_b32 v243, v155, v243
	ds_bpermute_b32 v244, v155, v244
	ds_bpermute_b32 v245, v155, v245
	s_waitcnt lgkmcnt(0)
	v_cndmask_b32_e64 v186, 0, v186, s[6:7]
	v_cndmask_b32_e64 v187, 0, v187, s[6:7]
	v_cndmask_b32_e64 v188, 0, v188, s[6:7]
	v_cndmask_b32_e64 v189, 0, v189, s[6:7]
	v_lshlrev_b32_e32 v130, 16, v182
	v_and_b32_e32 v131, 0xffff0000, v182
	v_lshlrev_b32_e32 v132, 16, v183
	v_and_b32_e32 v133, 0xffff0000, v183
	v_mul_f32_e32 v130, 0xbfb8aa3b, v130
	v_mul_f32_e32 v131, 0xbfb8aa3b, v131
	v_mul_f32_e32 v132, 0xbfb8aa3b, v132
	v_mul_f32_e32 v133, 0xbfb8aa3b, v133
	v_exp_f32_e32 v130, v130
	v_exp_f32_e32 v131, v131
	v_exp_f32_e32 v132, v132
	v_exp_f32_e32 v133, v133
	v_lshlrev_b32_e32 v134, 16, v186
	v_and_b32_e32 v135, 0xffff0000, v186
	v_lshlrev_b32_e32 v136, 16, v187
	v_and_b32_e32 v137, 0xffff0000, v187
	v_add_f32_e32 v130, 1.0, v130
	v_add_f32_e32 v131, 1.0, v131
	v_add_f32_e32 v132, 1.0, v132
	v_add_f32_e32 v133, 1.0, v133
	v_rcp_f32_e32 v130, v130
	v_rcp_f32_e32 v131, v131
	v_rcp_f32_e32 v132, v132
	v_rcp_f32_e32 v133, v133
	s_nop 0
	v_fmac_f32_e32 v134, v94, v130
	v_fmac_f32_e32 v135, v95, v131
	v_fmac_f32_e32 v136, v96, v132
	v_fmac_f32_e32 v137, v97, v133
	v_cvt_pk_bf16_f32 v94, v134, v135
	v_cvt_pk_bf16_f32 v95, v136, v137
	v_lshlrev_b32_e32 v130, 16, v184
	v_and_b32_e32 v131, 0xffff0000, v184
	v_lshlrev_b32_e32 v132, 16, v185
	v_and_b32_e32 v133, 0xffff0000, v185
	v_mul_f32_e32 v130, 0xbfb8aa3b, v130
	v_mul_f32_e32 v131, 0xbfb8aa3b, v131
	v_mul_f32_e32 v132, 0xbfb8aa3b, v132
	v_mul_f32_e32 v133, 0xbfb8aa3b, v133
	v_exp_f32_e32 v130, v130
	v_exp_f32_e32 v131, v131
	v_exp_f32_e32 v132, v132
	v_exp_f32_e32 v133, v133
	v_lshlrev_b32_e32 v134, 16, v188
	v_and_b32_e32 v135, 0xffff0000, v188
	v_lshlrev_b32_e32 v136, 16, v189
	v_and_b32_e32 v137, 0xffff0000, v189
	v_add_f32_e32 v130, 1.0, v130
	v_add_f32_e32 v131, 1.0, v131
	v_add_f32_e32 v132, 1.0, v132
	v_add_f32_e32 v133, 1.0, v133
	v_rcp_f32_e32 v130, v130
	v_rcp_f32_e32 v131, v131
	v_rcp_f32_e32 v132, v132
	v_rcp_f32_e32 v133, v133
	s_nop 0
	v_fmac_f32_e32 v134, v90, v130
	v_fmac_f32_e32 v135, v91, v131
	v_fmac_f32_e32 v136, v92, v132
	v_fmac_f32_e32 v137, v93, v133
	v_cvt_pk_bf16_f32 v96, v134, v135
	v_cvt_pk_bf16_f32 v97, v136, v137
	v_cndmask_b32_e64 v242, 0, v242, s[6:7]
	v_cndmask_b32_e64 v243, 0, v243, s[6:7]
	v_cndmask_b32_e64 v244, 0, v244, s[6:7]
	v_cndmask_b32_e64 v245, 0, v245, s[6:7]
	v_lshlrev_b32_e32 v130, 16, v190
	v_and_b32_e32 v131, 0xffff0000, v190
	v_lshlrev_b32_e32 v132, 16, v191
	v_and_b32_e32 v133, 0xffff0000, v191
	v_mul_f32_e32 v130, 0xbfb8aa3b, v130
	v_mul_f32_e32 v131, 0xbfb8aa3b, v131
	v_mul_f32_e32 v132, 0xbfb8aa3b, v132
	v_mul_f32_e32 v133, 0xbfb8aa3b, v133
	v_exp_f32_e32 v130, v130
	v_exp_f32_e32 v131, v131
	v_exp_f32_e32 v132, v132
	v_exp_f32_e32 v133, v133
	v_lshlrev_b32_e32 v134, 16, v242
	v_and_b32_e32 v135, 0xffff0000, v242
	v_lshlrev_b32_e32 v136, 16, v243
	v_and_b32_e32 v137, 0xffff0000, v243
	v_add_f32_e32 v130, 1.0, v130
	v_add_f32_e32 v131, 1.0, v131
	v_add_f32_e32 v132, 1.0, v132
	v_add_f32_e32 v133, 1.0, v133
	v_rcp_f32_e32 v130, v130
	v_rcp_f32_e32 v131, v131
	v_rcp_f32_e32 v132, v132
	v_rcp_f32_e32 v133, v133
	s_nop 0
	v_fmac_f32_e32 v134, v86, v130
	v_fmac_f32_e32 v135, v87, v131
	v_fmac_f32_e32 v136, v88, v132
	v_fmac_f32_e32 v137, v89, v133
	v_cvt_pk_bf16_f32 v86, v134, v135
	v_cvt_pk_bf16_f32 v87, v136, v137
	v_lshlrev_b32_e32 v130, 16, v192
	v_and_b32_e32 v131, 0xffff0000, v192
	v_lshlrev_b32_e32 v132, 16, v193
	v_and_b32_e32 v133, 0xffff0000, v193
	v_mul_f32_e32 v130, 0xbfb8aa3b, v130
	v_mul_f32_e32 v131, 0xbfb8aa3b, v131
	v_mul_f32_e32 v132, 0xbfb8aa3b, v132
	v_mul_f32_e32 v133, 0xbfb8aa3b, v133
	v_exp_f32_e32 v130, v130
	v_exp_f32_e32 v131, v131
	v_exp_f32_e32 v132, v132
	v_exp_f32_e32 v133, v133
	v_lshlrev_b32_e32 v134, 16, v244
	v_and_b32_e32 v135, 0xffff0000, v244
	v_lshlrev_b32_e32 v136, 16, v245
	v_and_b32_e32 v137, 0xffff0000, v245
	v_add_f32_e32 v130, 1.0, v130
	v_add_f32_e32 v131, 1.0, v131
	v_add_f32_e32 v132, 1.0, v132
	v_add_f32_e32 v133, 1.0, v133
	v_rcp_f32_e32 v130, v130
	v_rcp_f32_e32 v131, v131
	v_rcp_f32_e32 v132, v132
	v_rcp_f32_e32 v133, v133
	s_nop 0
	v_fmac_f32_e32 v134, v82, v130
	v_fmac_f32_e32 v135, v83, v131
	v_fmac_f32_e32 v136, v84, v132
	v_fmac_f32_e32 v137, v85, v133
	v_cvt_pk_bf16_f32 v88, v134, v135
	v_cvt_pk_bf16_f32 v89, v136, v137
	ds_bpermute_b32 v94, v156, v94
	ds_bpermute_b32 v95, v156, v95
	ds_bpermute_b32 v96, v156, v96
	ds_bpermute_b32 v97, v156, v97
	ds_bpermute_b32 v86, v156, v86
	ds_bpermute_b32 v87, v156, v87
	ds_bpermute_b32 v88, v156, v88
	ds_bpermute_b32 v89, v156, v89
	global_load_dwordx4 v[182:185], v[138:139], off
	global_load_dwordx4 v[186:189], v[140:141], off
	global_load_dwordx4 v[190:193], v[138:139], off offset:256
	global_load_dwordx4 v[242:245], v[140:141], off offset:256
	v_lshl_add_u64 v[138:139], v[138:139], 0, s[0:1]
	v_lshl_add_u64 v[140:141], v[140:141], 0, s[34:35]
	s_waitcnt lgkmcnt(0)
	global_store_dwordx4 v[142:143], v[94:97], off
	global_store_dwordx4 v[142:143], v[86:89], off offset:256
	v_lshl_add_u64 v[142:143], v[142:143], 0, s[34:35]
	s_waitcnt vmcnt(14)
	ds_bpermute_b32 v210, v155, v210
	ds_bpermute_b32 v211, v155, v211
	ds_bpermute_b32 v212, v155, v212
	ds_bpermute_b32 v213, v155, v213
	ds_bpermute_b32 v214, v155, v214
	ds_bpermute_b32 v215, v155, v215
	ds_bpermute_b32 v216, v155, v216
	ds_bpermute_b32 v217, v155, v217
	ds_bpermute_b32 v218, v155, v218
	ds_bpermute_b32 v219, v155, v219
	ds_bpermute_b32 v220, v155, v220
	ds_bpermute_b32 v221, v155, v221
	ds_bpermute_b32 v222, v155, v222
	ds_bpermute_b32 v223, v155, v223
	ds_bpermute_b32 v224, v155, v224
	ds_bpermute_b32 v225, v155, v225
	s_waitcnt lgkmcnt(0)
	v_cndmask_b32_e64 v214, 0, v214, s[6:7]
	v_cndmask_b32_e64 v215, 0, v215, s[6:7]
	v_cndmask_b32_e64 v216, 0, v216, s[6:7]
	v_cndmask_b32_e64 v217, 0, v217, s[6:7]
	v_lshlrev_b32_e32 v130, 16, v210
	v_and_b32_e32 v131, 0xffff0000, v210
	v_lshlrev_b32_e32 v132, 16, v211
	v_and_b32_e32 v133, 0xffff0000, v211
	v_mul_f32_e32 v130, 0xbfb8aa3b, v130
	v_mul_f32_e32 v131, 0xbfb8aa3b, v131
	v_mul_f32_e32 v132, 0xbfb8aa3b, v132
	v_mul_f32_e32 v133, 0xbfb8aa3b, v133
	v_exp_f32_e32 v130, v130
	v_exp_f32_e32 v131, v131
	v_exp_f32_e32 v132, v132
	v_exp_f32_e32 v133, v133
	v_lshlrev_b32_e32 v134, 16, v214
	v_and_b32_e32 v135, 0xffff0000, v214
	v_lshlrev_b32_e32 v136, 16, v215
	v_and_b32_e32 v137, 0xffff0000, v215
	v_add_f32_e32 v130, 1.0, v130
	v_add_f32_e32 v131, 1.0, v131
	v_add_f32_e32 v132, 1.0, v132
	v_add_f32_e32 v133, 1.0, v133
	v_rcp_f32_e32 v130, v130
	v_rcp_f32_e32 v131, v131
	v_rcp_f32_e32 v132, v132
	v_rcp_f32_e32 v133, v133
	s_nop 0
	v_fmac_f32_e32 v134, v78, v130
	v_fmac_f32_e32 v135, v79, v131
	v_fmac_f32_e32 v136, v80, v132
	v_fmac_f32_e32 v137, v81, v133
	v_cvt_pk_bf16_f32 v78, v134, v135
	v_cvt_pk_bf16_f32 v79, v136, v137
	v_lshlrev_b32_e32 v130, 16, v212
	v_and_b32_e32 v131, 0xffff0000, v212
	v_lshlrev_b32_e32 v132, 16, v213
	v_and_b32_e32 v133, 0xffff0000, v213
	v_mul_f32_e32 v130, 0xbfb8aa3b, v130
	v_mul_f32_e32 v131, 0xbfb8aa3b, v131
	v_mul_f32_e32 v132, 0xbfb8aa3b, v132
	v_mul_f32_e32 v133, 0xbfb8aa3b, v133
	v_exp_f32_e32 v130, v130
	v_exp_f32_e32 v131, v131
	v_exp_f32_e32 v132, v132
	v_exp_f32_e32 v133, v133
	v_lshlrev_b32_e32 v134, 16, v216
	v_and_b32_e32 v135, 0xffff0000, v216
	v_lshlrev_b32_e32 v136, 16, v217
	v_and_b32_e32 v137, 0xffff0000, v217
	v_add_f32_e32 v130, 1.0, v130
	v_add_f32_e32 v131, 1.0, v131
	v_add_f32_e32 v132, 1.0, v132
	v_add_f32_e32 v133, 1.0, v133
	v_rcp_f32_e32 v130, v130
	v_rcp_f32_e32 v131, v131
	v_rcp_f32_e32 v132, v132
	v_rcp_f32_e32 v133, v133
	s_nop 0
	v_fmac_f32_e32 v134, v74, v130
	v_fmac_f32_e32 v135, v75, v131
	v_fmac_f32_e32 v136, v76, v132
	v_fmac_f32_e32 v137, v77, v133
	v_cvt_pk_bf16_f32 v80, v134, v135
	v_cvt_pk_bf16_f32 v81, v136, v137
	v_cndmask_b32_e64 v222, 0, v222, s[6:7]
	v_cndmask_b32_e64 v223, 0, v223, s[6:7]
	v_cndmask_b32_e64 v224, 0, v224, s[6:7]
	v_cndmask_b32_e64 v225, 0, v225, s[6:7]
	v_lshlrev_b32_e32 v130, 16, v218
	v_and_b32_e32 v131, 0xffff0000, v218
	v_lshlrev_b32_e32 v132, 16, v219
	v_and_b32_e32 v133, 0xffff0000, v219
	v_mul_f32_e32 v130, 0xbfb8aa3b, v130
	v_mul_f32_e32 v131, 0xbfb8aa3b, v131
	v_mul_f32_e32 v132, 0xbfb8aa3b, v132
	v_mul_f32_e32 v133, 0xbfb8aa3b, v133
	v_exp_f32_e32 v130, v130
	v_exp_f32_e32 v131, v131
	v_exp_f32_e32 v132, v132
	v_exp_f32_e32 v133, v133
	v_lshlrev_b32_e32 v134, 16, v222
	v_and_b32_e32 v135, 0xffff0000, v222
	v_lshlrev_b32_e32 v136, 16, v223
	v_and_b32_e32 v137, 0xffff0000, v223
	v_add_f32_e32 v130, 1.0, v130
	v_add_f32_e32 v131, 1.0, v131
	v_add_f32_e32 v132, 1.0, v132
	v_add_f32_e32 v133, 1.0, v133
	v_rcp_f32_e32 v130, v130
	v_rcp_f32_e32 v131, v131
	v_rcp_f32_e32 v132, v132
	v_rcp_f32_e32 v133, v133
	s_nop 0
	v_fmac_f32_e32 v134, v70, v130
	v_fmac_f32_e32 v135, v71, v131
	v_fmac_f32_e32 v136, v72, v132
	v_fmac_f32_e32 v137, v73, v133
	v_cvt_pk_bf16_f32 v70, v134, v135
	v_cvt_pk_bf16_f32 v71, v136, v137
	v_lshlrev_b32_e32 v130, 16, v220
	v_and_b32_e32 v131, 0xffff0000, v220
	v_lshlrev_b32_e32 v132, 16, v221
	v_and_b32_e32 v133, 0xffff0000, v221
	v_mul_f32_e32 v130, 0xbfb8aa3b, v130
	v_mul_f32_e32 v131, 0xbfb8aa3b, v131
	v_mul_f32_e32 v132, 0xbfb8aa3b, v132
	v_mul_f32_e32 v133, 0xbfb8aa3b, v133
	v_exp_f32_e32 v130, v130
	v_exp_f32_e32 v131, v131
	v_exp_f32_e32 v132, v132
	v_exp_f32_e32 v133, v133
	v_lshlrev_b32_e32 v134, 16, v224
	v_and_b32_e32 v135, 0xffff0000, v224
	v_lshlrev_b32_e32 v136, 16, v225
	v_and_b32_e32 v137, 0xffff0000, v225
	v_add_f32_e32 v130, 1.0, v130
	v_add_f32_e32 v131, 1.0, v131
	v_add_f32_e32 v132, 1.0, v132
	v_add_f32_e32 v133, 1.0, v133
	v_rcp_f32_e32 v130, v130
	v_rcp_f32_e32 v131, v131
	v_rcp_f32_e32 v132, v132
	v_rcp_f32_e32 v133, v133
	s_nop 0
	v_fmac_f32_e32 v134, v66, v130
	v_fmac_f32_e32 v135, v67, v131
	v_fmac_f32_e32 v136, v68, v132
	v_fmac_f32_e32 v137, v69, v133
	v_cvt_pk_bf16_f32 v72, v134, v135
	v_cvt_pk_bf16_f32 v73, v136, v137
	ds_bpermute_b32 v78, v156, v78
	ds_bpermute_b32 v79, v156, v79
	ds_bpermute_b32 v80, v156, v80
	ds_bpermute_b32 v81, v156, v81
	ds_bpermute_b32 v70, v156, v70
	ds_bpermute_b32 v71, v156, v71
	ds_bpermute_b32 v72, v156, v72
	ds_bpermute_b32 v73, v156, v73
	global_load_dwordx4 v[210:213], v[138:139], off
	global_load_dwordx4 v[214:217], v[140:141], off
	global_load_dwordx4 v[218:221], v[138:139], off offset:256
	global_load_dwordx4 v[222:225], v[140:141], off offset:256
	v_lshl_add_u64 v[138:139], v[138:139], 0, s[0:1]
	v_lshl_add_u64 v[140:141], v[140:141], 0, s[34:35]
	s_waitcnt lgkmcnt(0)
	global_store_dwordx4 v[142:143], v[78:81], off
	global_store_dwordx4 v[142:143], v[70:73], off offset:256
	v_lshl_add_u64 v[142:143], v[142:143], 0, s[38:39]
	s_waitcnt vmcnt(14)
	ds_bpermute_b32 v226, v155, v226
	ds_bpermute_b32 v227, v155, v227
	ds_bpermute_b32 v228, v155, v228
	ds_bpermute_b32 v229, v155, v229
	ds_bpermute_b32 v230, v155, v230
	ds_bpermute_b32 v231, v155, v231
	ds_bpermute_b32 v232, v155, v232
	ds_bpermute_b32 v233, v155, v233
	ds_bpermute_b32 v234, v155, v234
	ds_bpermute_b32 v235, v155, v235
	ds_bpermute_b32 v236, v155, v236
	ds_bpermute_b32 v237, v155, v237
	ds_bpermute_b32 v238, v155, v238
	ds_bpermute_b32 v239, v155, v239
	ds_bpermute_b32 v240, v155, v240
	ds_bpermute_b32 v241, v155, v241
	s_waitcnt lgkmcnt(0)
	v_cndmask_b32_e64 v230, 0, v230, s[6:7]
	v_cndmask_b32_e64 v231, 0, v231, s[6:7]
	v_cndmask_b32_e64 v232, 0, v232, s[6:7]
	v_cndmask_b32_e64 v233, 0, v233, s[6:7]
	v_lshlrev_b32_e32 v130, 16, v226
	v_and_b32_e32 v131, 0xffff0000, v226
	v_lshlrev_b32_e32 v132, 16, v227
	v_and_b32_e32 v133, 0xffff0000, v227
	v_mul_f32_e32 v130, 0xbfb8aa3b, v130
	v_mul_f32_e32 v131, 0xbfb8aa3b, v131
	v_mul_f32_e32 v132, 0xbfb8aa3b, v132
	v_mul_f32_e32 v133, 0xbfb8aa3b, v133
	v_exp_f32_e32 v130, v130
	v_exp_f32_e32 v131, v131
	v_exp_f32_e32 v132, v132
	v_exp_f32_e32 v133, v133
	v_lshlrev_b32_e32 v134, 16, v230
	v_and_b32_e32 v135, 0xffff0000, v230
	v_lshlrev_b32_e32 v136, 16, v231
	v_and_b32_e32 v137, 0xffff0000, v231
	v_add_f32_e32 v130, 1.0, v130
	v_add_f32_e32 v131, 1.0, v131
	v_add_f32_e32 v132, 1.0, v132
	v_add_f32_e32 v133, 1.0, v133
	v_rcp_f32_e32 v130, v130
	v_rcp_f32_e32 v131, v131
	v_rcp_f32_e32 v132, v132
	v_rcp_f32_e32 v133, v133
	s_nop 0
	v_fmac_f32_e32 v134, v62, v130
	v_fmac_f32_e32 v135, v63, v131
	v_fmac_f32_e32 v136, v64, v132
	v_fmac_f32_e32 v137, v65, v133
	v_cvt_pk_bf16_f32 v62, v134, v135
	v_cvt_pk_bf16_f32 v63, v136, v137
	v_lshlrev_b32_e32 v130, 16, v228
	v_and_b32_e32 v131, 0xffff0000, v228
	v_lshlrev_b32_e32 v132, 16, v229
	v_and_b32_e32 v133, 0xffff0000, v229
	v_mul_f32_e32 v130, 0xbfb8aa3b, v130
	v_mul_f32_e32 v131, 0xbfb8aa3b, v131
	v_mul_f32_e32 v132, 0xbfb8aa3b, v132
	v_mul_f32_e32 v133, 0xbfb8aa3b, v133
	v_exp_f32_e32 v130, v130
	v_exp_f32_e32 v131, v131
	v_exp_f32_e32 v132, v132
	v_exp_f32_e32 v133, v133
	v_lshlrev_b32_e32 v134, 16, v232
	v_and_b32_e32 v135, 0xffff0000, v232
	v_lshlrev_b32_e32 v136, 16, v233
	v_and_b32_e32 v137, 0xffff0000, v233
	v_add_f32_e32 v130, 1.0, v130
	v_add_f32_e32 v131, 1.0, v131
	v_add_f32_e32 v132, 1.0, v132
	v_add_f32_e32 v133, 1.0, v133
	v_rcp_f32_e32 v130, v130
	v_rcp_f32_e32 v131, v131
	v_rcp_f32_e32 v132, v132
	v_rcp_f32_e32 v133, v133
	s_nop 0
	v_fmac_f32_e32 v134, v58, v130
	v_fmac_f32_e32 v135, v59, v131
	v_fmac_f32_e32 v136, v60, v132
	v_fmac_f32_e32 v137, v61, v133
	v_cvt_pk_bf16_f32 v64, v134, v135
	v_cvt_pk_bf16_f32 v65, v136, v137
	v_cndmask_b32_e64 v238, 0, v238, s[6:7]
	v_cndmask_b32_e64 v239, 0, v239, s[6:7]
	v_cndmask_b32_e64 v240, 0, v240, s[6:7]
	v_cndmask_b32_e64 v241, 0, v241, s[6:7]
	v_lshlrev_b32_e32 v130, 16, v234
	v_and_b32_e32 v131, 0xffff0000, v234
	v_lshlrev_b32_e32 v132, 16, v235
	v_and_b32_e32 v133, 0xffff0000, v235
	v_mul_f32_e32 v130, 0xbfb8aa3b, v130
	v_mul_f32_e32 v131, 0xbfb8aa3b, v131
	v_mul_f32_e32 v132, 0xbfb8aa3b, v132
	v_mul_f32_e32 v133, 0xbfb8aa3b, v133
	v_exp_f32_e32 v130, v130
	v_exp_f32_e32 v131, v131
	v_exp_f32_e32 v132, v132
	v_exp_f32_e32 v133, v133
	v_lshlrev_b32_e32 v134, 16, v238
	v_and_b32_e32 v135, 0xffff0000, v238
	v_lshlrev_b32_e32 v136, 16, v239
	v_and_b32_e32 v137, 0xffff0000, v239
	v_add_f32_e32 v130, 1.0, v130
	v_add_f32_e32 v131, 1.0, v131
	v_add_f32_e32 v132, 1.0, v132
	v_add_f32_e32 v133, 1.0, v133
	v_rcp_f32_e32 v130, v130
	v_rcp_f32_e32 v131, v131
	v_rcp_f32_e32 v132, v132
	v_rcp_f32_e32 v133, v133
	s_nop 0
	v_fmac_f32_e32 v134, v54, v130
	v_fmac_f32_e32 v135, v55, v131
	v_fmac_f32_e32 v136, v56, v132
	v_fmac_f32_e32 v137, v57, v133
	v_cvt_pk_bf16_f32 v54, v134, v135
	v_cvt_pk_bf16_f32 v55, v136, v137
	v_lshlrev_b32_e32 v130, 16, v236
	v_and_b32_e32 v131, 0xffff0000, v236
	v_lshlrev_b32_e32 v132, 16, v237
	v_and_b32_e32 v133, 0xffff0000, v237
	v_mul_f32_e32 v130, 0xbfb8aa3b, v130
	v_mul_f32_e32 v131, 0xbfb8aa3b, v131
	v_mul_f32_e32 v132, 0xbfb8aa3b, v132
	v_mul_f32_e32 v133, 0xbfb8aa3b, v133
	v_exp_f32_e32 v130, v130
	v_exp_f32_e32 v131, v131
	v_exp_f32_e32 v132, v132
	v_exp_f32_e32 v133, v133
	v_lshlrev_b32_e32 v134, 16, v240
	v_and_b32_e32 v135, 0xffff0000, v240
	v_lshlrev_b32_e32 v136, 16, v241
	v_and_b32_e32 v137, 0xffff0000, v241
	v_add_f32_e32 v130, 1.0, v130
	v_add_f32_e32 v131, 1.0, v131
	v_add_f32_e32 v132, 1.0, v132
	v_add_f32_e32 v133, 1.0, v133
	v_rcp_f32_e32 v130, v130
	v_rcp_f32_e32 v131, v131
	v_rcp_f32_e32 v132, v132
	v_rcp_f32_e32 v133, v133
	s_nop 0
	v_fmac_f32_e32 v134, v50, v130
	v_fmac_f32_e32 v135, v51, v131
	v_fmac_f32_e32 v136, v52, v132
	v_fmac_f32_e32 v137, v53, v133
	v_cvt_pk_bf16_f32 v56, v134, v135
	v_cvt_pk_bf16_f32 v57, v136, v137
	ds_bpermute_b32 v62, v156, v62
	ds_bpermute_b32 v63, v156, v63
	ds_bpermute_b32 v64, v156, v64
	ds_bpermute_b32 v65, v156, v65
	ds_bpermute_b32 v54, v156, v54
	ds_bpermute_b32 v55, v156, v55
	ds_bpermute_b32 v56, v156, v56
	ds_bpermute_b32 v57, v156, v57
	global_load_dwordx4 v[226:229], v[138:139], off
	global_load_dwordx4 v[230:233], v[140:141], off
	global_load_dwordx4 v[234:237], v[138:139], off offset:256
	global_load_dwordx4 v[238:241], v[140:141], off offset:256
	s_waitcnt lgkmcnt(0)
	global_store_dwordx4 v[142:143], v[62:65], off
	global_store_dwordx4 v[142:143], v[54:57], off offset:256
	v_lshl_add_u64 v[142:143], v[142:143], 0, s[34:35]
	s_waitcnt vmcnt(14)
	ds_bpermute_b32 v182, v155, v182
	ds_bpermute_b32 v183, v155, v183
	ds_bpermute_b32 v184, v155, v184
	ds_bpermute_b32 v185, v155, v185
	ds_bpermute_b32 v186, v155, v186
	ds_bpermute_b32 v187, v155, v187
	ds_bpermute_b32 v188, v155, v188
	ds_bpermute_b32 v189, v155, v189
	ds_bpermute_b32 v190, v155, v190
	ds_bpermute_b32 v191, v155, v191
	ds_bpermute_b32 v192, v155, v192
	ds_bpermute_b32 v193, v155, v193
	ds_bpermute_b32 v242, v155, v242
	ds_bpermute_b32 v243, v155, v243
	ds_bpermute_b32 v244, v155, v244
	ds_bpermute_b32 v245, v155, v245
	s_waitcnt lgkmcnt(0)
	v_cndmask_b32_e64 v186, 0, v186, s[6:7]
	v_cndmask_b32_e64 v187, 0, v187, s[6:7]
	v_cndmask_b32_e64 v188, 0, v188, s[6:7]
	v_cndmask_b32_e64 v189, 0, v189, s[6:7]
	v_lshlrev_b32_e32 v130, 16, v182
	v_and_b32_e32 v131, 0xffff0000, v182
	v_lshlrev_b32_e32 v132, 16, v183
	v_and_b32_e32 v133, 0xffff0000, v183
	v_mul_f32_e32 v130, 0xbfb8aa3b, v130
	v_mul_f32_e32 v131, 0xbfb8aa3b, v131
	v_mul_f32_e32 v132, 0xbfb8aa3b, v132
	v_mul_f32_e32 v133, 0xbfb8aa3b, v133
	v_exp_f32_e32 v130, v130
	v_exp_f32_e32 v131, v131
	v_exp_f32_e32 v132, v132
	v_exp_f32_e32 v133, v133
	v_lshlrev_b32_e32 v134, 16, v186
	v_and_b32_e32 v135, 0xffff0000, v186
	v_lshlrev_b32_e32 v136, 16, v187
	v_and_b32_e32 v137, 0xffff0000, v187
	v_add_f32_e32 v130, 1.0, v130
	v_add_f32_e32 v131, 1.0, v131
	v_add_f32_e32 v132, 1.0, v132
	v_add_f32_e32 v133, 1.0, v133
	v_rcp_f32_e32 v130, v130
	v_rcp_f32_e32 v131, v131
	v_rcp_f32_e32 v132, v132
	v_rcp_f32_e32 v133, v133
	s_nop 0
	v_fmac_f32_e32 v134, v46, v130
	v_fmac_f32_e32 v135, v47, v131
	v_fmac_f32_e32 v136, v48, v132
	v_fmac_f32_e32 v137, v49, v133
	v_cvt_pk_bf16_f32 v46, v134, v135
	v_cvt_pk_bf16_f32 v47, v136, v137
	v_lshlrev_b32_e32 v130, 16, v184
	v_and_b32_e32 v131, 0xffff0000, v184
	v_lshlrev_b32_e32 v132, 16, v185
	v_and_b32_e32 v133, 0xffff0000, v185
	v_mul_f32_e32 v130, 0xbfb8aa3b, v130
	v_mul_f32_e32 v131, 0xbfb8aa3b, v131
	v_mul_f32_e32 v132, 0xbfb8aa3b, v132
	v_mul_f32_e32 v133, 0xbfb8aa3b, v133
	v_exp_f32_e32 v130, v130
	v_exp_f32_e32 v131, v131
	v_exp_f32_e32 v132, v132
	v_exp_f32_e32 v133, v133
	v_lshlrev_b32_e32 v134, 16, v188
	v_and_b32_e32 v135, 0xffff0000, v188
	v_lshlrev_b32_e32 v136, 16, v189
	v_and_b32_e32 v137, 0xffff0000, v189
	v_add_f32_e32 v130, 1.0, v130
	v_add_f32_e32 v131, 1.0, v131
	v_add_f32_e32 v132, 1.0, v132
	v_add_f32_e32 v133, 1.0, v133
	v_rcp_f32_e32 v130, v130
	v_rcp_f32_e32 v131, v131
	v_rcp_f32_e32 v132, v132
	v_rcp_f32_e32 v133, v133
	s_nop 0
	v_fmac_f32_e32 v134, v42, v130
	v_fmac_f32_e32 v135, v43, v131
	v_fmac_f32_e32 v136, v44, v132
	v_fmac_f32_e32 v137, v45, v133
	v_cvt_pk_bf16_f32 v48, v134, v135
	v_cvt_pk_bf16_f32 v49, v136, v137
	v_cndmask_b32_e64 v242, 0, v242, s[6:7]
	v_cndmask_b32_e64 v243, 0, v243, s[6:7]
	v_cndmask_b32_e64 v244, 0, v244, s[6:7]
	v_cndmask_b32_e64 v245, 0, v245, s[6:7]
	v_lshlrev_b32_e32 v130, 16, v190
	v_and_b32_e32 v131, 0xffff0000, v190
	v_lshlrev_b32_e32 v132, 16, v191
	v_and_b32_e32 v133, 0xffff0000, v191
	v_mul_f32_e32 v130, 0xbfb8aa3b, v130
	v_mul_f32_e32 v131, 0xbfb8aa3b, v131
	v_mul_f32_e32 v132, 0xbfb8aa3b, v132
	v_mul_f32_e32 v133, 0xbfb8aa3b, v133
	v_exp_f32_e32 v130, v130
	v_exp_f32_e32 v131, v131
	v_exp_f32_e32 v132, v132
	v_exp_f32_e32 v133, v133
	v_lshlrev_b32_e32 v134, 16, v242
	v_and_b32_e32 v135, 0xffff0000, v242
	v_lshlrev_b32_e32 v136, 16, v243
	v_and_b32_e32 v137, 0xffff0000, v243
	v_add_f32_e32 v130, 1.0, v130
	v_add_f32_e32 v131, 1.0, v131
	v_add_f32_e32 v132, 1.0, v132
	v_add_f32_e32 v133, 1.0, v133
	v_rcp_f32_e32 v130, v130
	v_rcp_f32_e32 v131, v131
	v_rcp_f32_e32 v132, v132
	v_rcp_f32_e32 v133, v133
	s_nop 0
	v_fmac_f32_e32 v134, v38, v130
	v_fmac_f32_e32 v135, v39, v131
	v_fmac_f32_e32 v136, v40, v132
	v_fmac_f32_e32 v137, v41, v133
	v_cvt_pk_bf16_f32 v38, v134, v135
	v_cvt_pk_bf16_f32 v39, v136, v137
	v_lshlrev_b32_e32 v130, 16, v192
	v_and_b32_e32 v131, 0xffff0000, v192
	v_lshlrev_b32_e32 v132, 16, v193
	v_and_b32_e32 v133, 0xffff0000, v193
	v_mul_f32_e32 v130, 0xbfb8aa3b, v130
	v_mul_f32_e32 v131, 0xbfb8aa3b, v131
	v_mul_f32_e32 v132, 0xbfb8aa3b, v132
	v_mul_f32_e32 v133, 0xbfb8aa3b, v133
	v_exp_f32_e32 v130, v130
	v_exp_f32_e32 v131, v131
	v_exp_f32_e32 v132, v132
	v_exp_f32_e32 v133, v133
	v_lshlrev_b32_e32 v134, 16, v244
	v_and_b32_e32 v135, 0xffff0000, v244
	v_lshlrev_b32_e32 v136, 16, v245
	v_and_b32_e32 v137, 0xffff0000, v245
	v_add_f32_e32 v130, 1.0, v130
	v_add_f32_e32 v131, 1.0, v131
	v_add_f32_e32 v132, 1.0, v132
	v_add_f32_e32 v133, 1.0, v133
	v_rcp_f32_e32 v130, v130
	v_rcp_f32_e32 v131, v131
	v_rcp_f32_e32 v132, v132
	v_rcp_f32_e32 v133, v133
	s_nop 0
	v_fmac_f32_e32 v134, v34, v130
	v_fmac_f32_e32 v135, v35, v131
	v_fmac_f32_e32 v136, v36, v132
	v_fmac_f32_e32 v137, v37, v133
	v_cvt_pk_bf16_f32 v40, v134, v135
	v_cvt_pk_bf16_f32 v41, v136, v137
	ds_bpermute_b32 v46, v156, v46
	ds_bpermute_b32 v47, v156, v47
	ds_bpermute_b32 v48, v156, v48
	ds_bpermute_b32 v49, v156, v49
	ds_bpermute_b32 v38, v156, v38
	ds_bpermute_b32 v39, v156, v39
	ds_bpermute_b32 v40, v156, v40
	ds_bpermute_b32 v41, v156, v41
	s_waitcnt lgkmcnt(0)
	global_store_dwordx4 v[142:143], v[46:49], off
	global_store_dwordx4 v[142:143], v[38:41], off offset:256
	v_lshl_add_u64 v[142:143], v[142:143], 0, s[34:35]
	s_waitcnt vmcnt(10)
	ds_bpermute_b32 v210, v155, v210
	ds_bpermute_b32 v211, v155, v211
	ds_bpermute_b32 v212, v155, v212
	ds_bpermute_b32 v213, v155, v213
	ds_bpermute_b32 v214, v155, v214
	ds_bpermute_b32 v215, v155, v215
	ds_bpermute_b32 v216, v155, v216
	ds_bpermute_b32 v217, v155, v217
	ds_bpermute_b32 v218, v155, v218
	ds_bpermute_b32 v219, v155, v219
	ds_bpermute_b32 v220, v155, v220
	ds_bpermute_b32 v221, v155, v221
	ds_bpermute_b32 v222, v155, v222
	ds_bpermute_b32 v223, v155, v223
	ds_bpermute_b32 v224, v155, v224
	ds_bpermute_b32 v225, v155, v225
	s_waitcnt lgkmcnt(0)
	v_cndmask_b32_e64 v214, 0, v214, s[6:7]
	v_cndmask_b32_e64 v215, 0, v215, s[6:7]
	v_cndmask_b32_e64 v216, 0, v216, s[6:7]
	v_cndmask_b32_e64 v217, 0, v217, s[6:7]
	v_lshlrev_b32_e32 v130, 16, v210
	v_and_b32_e32 v131, 0xffff0000, v210
	v_lshlrev_b32_e32 v132, 16, v211
	v_and_b32_e32 v133, 0xffff0000, v211
	v_mul_f32_e32 v130, 0xbfb8aa3b, v130
	v_mul_f32_e32 v131, 0xbfb8aa3b, v131
	v_mul_f32_e32 v132, 0xbfb8aa3b, v132
	v_mul_f32_e32 v133, 0xbfb8aa3b, v133
	v_exp_f32_e32 v130, v130
	v_exp_f32_e32 v131, v131
	v_exp_f32_e32 v132, v132
	v_exp_f32_e32 v133, v133
	v_lshlrev_b32_e32 v134, 16, v214
	v_and_b32_e32 v135, 0xffff0000, v214
	v_lshlrev_b32_e32 v136, 16, v215
	v_and_b32_e32 v137, 0xffff0000, v215
	v_add_f32_e32 v130, 1.0, v130
	v_add_f32_e32 v131, 1.0, v131
	v_add_f32_e32 v132, 1.0, v132
	v_add_f32_e32 v133, 1.0, v133
	v_rcp_f32_e32 v130, v130
	v_rcp_f32_e32 v131, v131
	v_rcp_f32_e32 v132, v132
	v_rcp_f32_e32 v133, v133
	s_nop 0
	v_fmac_f32_e32 v134, v30, v130
	v_fmac_f32_e32 v135, v31, v131
	v_fmac_f32_e32 v136, v32, v132
	v_fmac_f32_e32 v137, v33, v133
	v_cvt_pk_bf16_f32 v30, v134, v135
	v_cvt_pk_bf16_f32 v31, v136, v137
	v_lshlrev_b32_e32 v130, 16, v212
	v_and_b32_e32 v131, 0xffff0000, v212
	v_lshlrev_b32_e32 v132, 16, v213
	v_and_b32_e32 v133, 0xffff0000, v213
	v_mul_f32_e32 v130, 0xbfb8aa3b, v130
	v_mul_f32_e32 v131, 0xbfb8aa3b, v131
	v_mul_f32_e32 v132, 0xbfb8aa3b, v132
	v_mul_f32_e32 v133, 0xbfb8aa3b, v133
	v_exp_f32_e32 v130, v130
	v_exp_f32_e32 v131, v131
	v_exp_f32_e32 v132, v132
	v_exp_f32_e32 v133, v133
	v_lshlrev_b32_e32 v134, 16, v216
	v_and_b32_e32 v135, 0xffff0000, v216
	v_lshlrev_b32_e32 v136, 16, v217
	v_and_b32_e32 v137, 0xffff0000, v217
	v_add_f32_e32 v130, 1.0, v130
	v_add_f32_e32 v131, 1.0, v131
	v_add_f32_e32 v132, 1.0, v132
	v_add_f32_e32 v133, 1.0, v133
	v_rcp_f32_e32 v130, v130
	v_rcp_f32_e32 v131, v131
	v_rcp_f32_e32 v132, v132
	v_rcp_f32_e32 v133, v133
	s_nop 0
	v_fmac_f32_e32 v134, v26, v130
	v_fmac_f32_e32 v135, v27, v131
	v_fmac_f32_e32 v136, v28, v132
	v_fmac_f32_e32 v137, v29, v133
	v_cvt_pk_bf16_f32 v32, v134, v135
	v_cvt_pk_bf16_f32 v33, v136, v137
	v_cndmask_b32_e64 v222, 0, v222, s[6:7]
	v_cndmask_b32_e64 v223, 0, v223, s[6:7]
	v_cndmask_b32_e64 v224, 0, v224, s[6:7]
	v_cndmask_b32_e64 v225, 0, v225, s[6:7]
	v_lshlrev_b32_e32 v130, 16, v218
	v_and_b32_e32 v131, 0xffff0000, v218
	v_lshlrev_b32_e32 v132, 16, v219
	v_and_b32_e32 v133, 0xffff0000, v219
	v_mul_f32_e32 v130, 0xbfb8aa3b, v130
	v_mul_f32_e32 v131, 0xbfb8aa3b, v131
	v_mul_f32_e32 v132, 0xbfb8aa3b, v132
	v_mul_f32_e32 v133, 0xbfb8aa3b, v133
	v_exp_f32_e32 v130, v130
	v_exp_f32_e32 v131, v131
	v_exp_f32_e32 v132, v132
	v_exp_f32_e32 v133, v133
	v_lshlrev_b32_e32 v134, 16, v222
	v_and_b32_e32 v135, 0xffff0000, v222
	v_lshlrev_b32_e32 v136, 16, v223
	v_and_b32_e32 v137, 0xffff0000, v223
	v_add_f32_e32 v130, 1.0, v130
	v_add_f32_e32 v131, 1.0, v131
	v_add_f32_e32 v132, 1.0, v132
	v_add_f32_e32 v133, 1.0, v133
	v_rcp_f32_e32 v130, v130
	v_rcp_f32_e32 v131, v131
	v_rcp_f32_e32 v132, v132
	v_rcp_f32_e32 v133, v133
	s_nop 0
	v_fmac_f32_e32 v134, v22, v130
	v_fmac_f32_e32 v135, v23, v131
	v_fmac_f32_e32 v136, v24, v132
	v_fmac_f32_e32 v137, v25, v133
	v_cvt_pk_bf16_f32 v22, v134, v135
	v_cvt_pk_bf16_f32 v23, v136, v137
	v_lshlrev_b32_e32 v130, 16, v220
	v_and_b32_e32 v131, 0xffff0000, v220
	v_lshlrev_b32_e32 v132, 16, v221
	v_and_b32_e32 v133, 0xffff0000, v221
	v_mul_f32_e32 v130, 0xbfb8aa3b, v130
	v_mul_f32_e32 v131, 0xbfb8aa3b, v131
	v_mul_f32_e32 v132, 0xbfb8aa3b, v132
	v_mul_f32_e32 v133, 0xbfb8aa3b, v133
	v_exp_f32_e32 v130, v130
	v_exp_f32_e32 v131, v131
	v_exp_f32_e32 v132, v132
	v_exp_f32_e32 v133, v133
	v_lshlrev_b32_e32 v134, 16, v224
	v_and_b32_e32 v135, 0xffff0000, v224
	v_lshlrev_b32_e32 v136, 16, v225
	v_and_b32_e32 v137, 0xffff0000, v225
	v_add_f32_e32 v130, 1.0, v130
	v_add_f32_e32 v131, 1.0, v131
	v_add_f32_e32 v132, 1.0, v132
	v_add_f32_e32 v133, 1.0, v133
	v_rcp_f32_e32 v130, v130
	v_rcp_f32_e32 v131, v131
	v_rcp_f32_e32 v132, v132
	v_rcp_f32_e32 v133, v133
	s_nop 0
	v_fmac_f32_e32 v134, v18, v130
	v_fmac_f32_e32 v135, v19, v131
	v_fmac_f32_e32 v136, v20, v132
	v_fmac_f32_e32 v137, v21, v133
	v_cvt_pk_bf16_f32 v24, v134, v135
	v_cvt_pk_bf16_f32 v25, v136, v137
	ds_bpermute_b32 v30, v156, v30
	ds_bpermute_b32 v31, v156, v31
	ds_bpermute_b32 v32, v156, v32
	ds_bpermute_b32 v33, v156, v33
	ds_bpermute_b32 v22, v156, v22
	ds_bpermute_b32 v23, v156, v23
	ds_bpermute_b32 v24, v156, v24
	ds_bpermute_b32 v25, v156, v25
	s_waitcnt lgkmcnt(0)
	global_store_dwordx4 v[142:143], v[30:33], off
	global_store_dwordx4 v[142:143], v[22:25], off offset:256
	v_lshl_add_u64 v[142:143], v[142:143], 0, s[34:35]
	s_waitcnt vmcnt(6)
	ds_bpermute_b32 v226, v155, v226
	ds_bpermute_b32 v227, v155, v227
	ds_bpermute_b32 v228, v155, v228
	ds_bpermute_b32 v229, v155, v229
	ds_bpermute_b32 v230, v155, v230
	ds_bpermute_b32 v231, v155, v231
	ds_bpermute_b32 v232, v155, v232
	ds_bpermute_b32 v233, v155, v233
	ds_bpermute_b32 v234, v155, v234
	ds_bpermute_b32 v235, v155, v235
	ds_bpermute_b32 v236, v155, v236
	ds_bpermute_b32 v237, v155, v237
	ds_bpermute_b32 v238, v155, v238
	ds_bpermute_b32 v239, v155, v239
	ds_bpermute_b32 v240, v155, v240
	ds_bpermute_b32 v241, v155, v241
	s_waitcnt lgkmcnt(0)
	v_cndmask_b32_e64 v230, 0, v230, s[6:7]
	v_cndmask_b32_e64 v231, 0, v231, s[6:7]
	v_cndmask_b32_e64 v232, 0, v232, s[6:7]
	v_cndmask_b32_e64 v233, 0, v233, s[6:7]
	v_lshlrev_b32_e32 v130, 16, v226
	v_and_b32_e32 v131, 0xffff0000, v226
	v_lshlrev_b32_e32 v132, 16, v227
	v_and_b32_e32 v133, 0xffff0000, v227
	v_mul_f32_e32 v130, 0xbfb8aa3b, v130
	v_mul_f32_e32 v131, 0xbfb8aa3b, v131
	v_mul_f32_e32 v132, 0xbfb8aa3b, v132
	v_mul_f32_e32 v133, 0xbfb8aa3b, v133
	v_exp_f32_e32 v130, v130
	v_exp_f32_e32 v131, v131
	v_exp_f32_e32 v132, v132
	v_exp_f32_e32 v133, v133
	v_lshlrev_b32_e32 v134, 16, v230
	v_and_b32_e32 v135, 0xffff0000, v230
	v_lshlrev_b32_e32 v136, 16, v231
	v_and_b32_e32 v137, 0xffff0000, v231
	v_add_f32_e32 v130, 1.0, v130
	v_add_f32_e32 v131, 1.0, v131
	v_add_f32_e32 v132, 1.0, v132
	v_add_f32_e32 v133, 1.0, v133
	v_rcp_f32_e32 v130, v130
	v_rcp_f32_e32 v131, v131
	v_rcp_f32_e32 v132, v132
	v_rcp_f32_e32 v133, v133
	s_nop 0
	v_fmac_f32_e32 v134, v14, v130
	v_fmac_f32_e32 v135, v15, v131
	v_fmac_f32_e32 v136, v16, v132
	v_fmac_f32_e32 v137, v17, v133
	v_cvt_pk_bf16_f32 v14, v134, v135
	v_cvt_pk_bf16_f32 v15, v136, v137
	v_lshlrev_b32_e32 v130, 16, v228
	v_and_b32_e32 v131, 0xffff0000, v228
	v_lshlrev_b32_e32 v132, 16, v229
	v_and_b32_e32 v133, 0xffff0000, v229
	v_mul_f32_e32 v130, 0xbfb8aa3b, v130
	v_mul_f32_e32 v131, 0xbfb8aa3b, v131
	v_mul_f32_e32 v132, 0xbfb8aa3b, v132
	v_mul_f32_e32 v133, 0xbfb8aa3b, v133
	v_exp_f32_e32 v130, v130
	v_exp_f32_e32 v131, v131
	v_exp_f32_e32 v132, v132
	v_exp_f32_e32 v133, v133
	v_lshlrev_b32_e32 v134, 16, v232
	v_and_b32_e32 v135, 0xffff0000, v232
	v_lshlrev_b32_e32 v136, 16, v233
	v_and_b32_e32 v137, 0xffff0000, v233
	v_add_f32_e32 v130, 1.0, v130
	v_add_f32_e32 v131, 1.0, v131
	v_add_f32_e32 v132, 1.0, v132
	v_add_f32_e32 v133, 1.0, v133
	v_rcp_f32_e32 v130, v130
	v_rcp_f32_e32 v131, v131
	v_rcp_f32_e32 v132, v132
	v_rcp_f32_e32 v133, v133
	s_nop 0
	v_fmac_f32_e32 v134, v10, v130
	v_fmac_f32_e32 v135, v11, v131
	v_fmac_f32_e32 v136, v12, v132
	v_fmac_f32_e32 v137, v13, v133
	v_cvt_pk_bf16_f32 v16, v134, v135
	v_cvt_pk_bf16_f32 v17, v136, v137
	v_cndmask_b32_e64 v238, 0, v238, s[6:7]
	v_cndmask_b32_e64 v239, 0, v239, s[6:7]
	v_cndmask_b32_e64 v240, 0, v240, s[6:7]
	v_cndmask_b32_e64 v241, 0, v241, s[6:7]
	v_lshlrev_b32_e32 v130, 16, v234
	v_and_b32_e32 v131, 0xffff0000, v234
	v_lshlrev_b32_e32 v132, 16, v235
	v_and_b32_e32 v133, 0xffff0000, v235
	v_mul_f32_e32 v130, 0xbfb8aa3b, v130
	v_mul_f32_e32 v131, 0xbfb8aa3b, v131
	v_mul_f32_e32 v132, 0xbfb8aa3b, v132
	v_mul_f32_e32 v133, 0xbfb8aa3b, v133
	v_exp_f32_e32 v130, v130
	v_exp_f32_e32 v131, v131
	v_exp_f32_e32 v132, v132
	v_exp_f32_e32 v133, v133
	v_lshlrev_b32_e32 v134, 16, v238
	v_and_b32_e32 v135, 0xffff0000, v238
	v_lshlrev_b32_e32 v136, 16, v239
	v_and_b32_e32 v137, 0xffff0000, v239
	v_add_f32_e32 v130, 1.0, v130
	v_add_f32_e32 v131, 1.0, v131
	v_add_f32_e32 v132, 1.0, v132
	v_add_f32_e32 v133, 1.0, v133
	v_rcp_f32_e32 v130, v130
	v_rcp_f32_e32 v131, v131
	v_rcp_f32_e32 v132, v132
	v_rcp_f32_e32 v133, v133
	s_nop 0
	v_fmac_f32_e32 v134, v6, v130
	v_fmac_f32_e32 v135, v7, v131
	v_fmac_f32_e32 v136, v8, v132
	v_fmac_f32_e32 v137, v9, v133
	v_cvt_pk_bf16_f32 v6, v134, v135
	v_cvt_pk_bf16_f32 v7, v136, v137
	v_lshlrev_b32_e32 v130, 16, v236
	v_and_b32_e32 v131, 0xffff0000, v236
	v_lshlrev_b32_e32 v132, 16, v237
	v_and_b32_e32 v133, 0xffff0000, v237
	v_mul_f32_e32 v130, 0xbfb8aa3b, v130
	v_mul_f32_e32 v131, 0xbfb8aa3b, v131
	v_mul_f32_e32 v132, 0xbfb8aa3b, v132
	v_mul_f32_e32 v133, 0xbfb8aa3b, v133
	v_exp_f32_e32 v130, v130
	v_exp_f32_e32 v131, v131
	v_exp_f32_e32 v132, v132
	v_exp_f32_e32 v133, v133
	v_lshlrev_b32_e32 v134, 16, v240
	v_and_b32_e32 v135, 0xffff0000, v240
	v_lshlrev_b32_e32 v136, 16, v241
	v_and_b32_e32 v137, 0xffff0000, v241
	v_add_f32_e32 v130, 1.0, v130
	v_add_f32_e32 v131, 1.0, v131
	v_add_f32_e32 v132, 1.0, v132
	v_add_f32_e32 v133, 1.0, v133
	v_rcp_f32_e32 v130, v130
	v_rcp_f32_e32 v131, v131
	v_rcp_f32_e32 v132, v132
	v_rcp_f32_e32 v133, v133
	s_nop 0
	v_fmac_f32_e32 v134, v2, v130
	v_fmac_f32_e32 v135, v3, v131
	v_fmac_f32_e32 v136, v4, v132
	v_fmac_f32_e32 v137, v5, v133
	v_cvt_pk_bf16_f32 v8, v134, v135
	v_cvt_pk_bf16_f32 v9, v136, v137
	ds_bpermute_b32 v14, v156, v14
	ds_bpermute_b32 v15, v156, v15
	ds_bpermute_b32 v16, v156, v16
	ds_bpermute_b32 v17, v156, v17
	ds_bpermute_b32 v6, v156, v6
	ds_bpermute_b32 v7, v156, v7
	ds_bpermute_b32 v8, v156, v8
	ds_bpermute_b32 v9, v156, v9
	s_waitcnt lgkmcnt(0)
	global_store_dwordx4 v[142:143], v[14:17], off
	global_store_dwordx4 v[142:143], v[6:9], off offset:256
	s_movk_i32 s8, 0xfa00
	s_mov_b32 s9, -1
	s_mov_b64 s[0:1], -1
	s_and_b64 vcc, exec, s[40:41]
	s_cbranch_vccnz .LBB0_194
	s_andn2_b64 vcc, exec, s[24:25]
	v_mov_b64 v[126:127], 0
	v_mov_b64 v[128:129], 0
	v_mov_b64 v[122:123], 0
	v_mov_b64 v[124:125], 0
	v_mov_b64 v[110:111], 0
	v_mov_b64 v[112:113], 0
	v_mov_b64 v[106:107], 0
	v_mov_b64 v[108:109], 0
	v_mov_b64 v[94:95], 0
	v_mov_b64 v[96:97], 0
	v_mov_b64 v[90:91], 0
	v_mov_b64 v[92:93], 0
	v_mov_b64 v[78:79], 0
	v_mov_b64 v[80:81], 0
	v_mov_b64 v[74:75], 0
	v_mov_b64 v[76:77], 0
	v_mov_b64 v[118:119], 0
	v_mov_b64 v[120:121], 0
	v_mov_b64 v[114:115], 0
	v_mov_b64 v[116:117], 0
	v_mov_b64 v[102:103], 0
	v_mov_b64 v[104:105], 0
	v_mov_b64 v[98:99], 0
	v_mov_b64 v[100:101], 0
	v_mov_b64 v[86:87], 0
	v_mov_b64 v[88:89], 0
	v_mov_b64 v[82:83], 0
	v_mov_b64 v[84:85], 0
	v_mov_b64 v[70:71], 0
	v_mov_b64 v[72:73], 0
	v_mov_b64 v[66:67], 0
	v_mov_b64 v[68:69], 0
	v_mov_b64 v[62:63], 0
	v_mov_b64 v[64:65], 0
	v_mov_b64 v[58:59], 0
	v_mov_b64 v[60:61], 0
	v_mov_b64 v[46:47], 0
	v_mov_b64 v[48:49], 0
	v_mov_b64 v[42:43], 0
	v_mov_b64 v[44:45], 0
	v_mov_b64 v[30:31], 0
	v_mov_b64 v[32:33], 0
	v_mov_b64 v[26:27], 0
	v_mov_b64 v[28:29], 0
	v_mov_b64 v[14:15], 0
	v_mov_b64 v[16:17], 0
	v_mov_b64 v[10:11], 0
	v_mov_b64 v[12:13], 0
	v_mov_b64 v[54:55], 0
	v_mov_b64 v[56:57], 0
	v_mov_b64 v[50:51], 0
	v_mov_b64 v[52:53], 0
	v_mov_b64 v[38:39], 0
	v_mov_b64 v[40:41], 0
	v_mov_b64 v[34:35], 0
	v_mov_b64 v[36:37], 0
	v_mov_b64 v[22:23], 0
	v_mov_b64 v[24:25], 0
	v_mov_b64 v[18:19], 0
	v_mov_b64 v[20:21], 0
	v_mov_b64 v[6:7], 0
	v_mov_b64 v[8:9], 0
	v_mov_b64 v[2:3], 0
	v_mov_b64 v[4:5], 0
	s_cbranch_vccnz .LBB0_193
	s_barrier
	s_branch .LBB0_193
